# ev_in/odin bf16 row-major outputs without LDS staging: DPP + v_perm lane-pair packing, 32 direct dword stores per wave-tile (4 rows x 64 B each) instead of LDS strip + 8 dwordx4 stores
# baseline (speedup 1.0000x reference)
.Levin1_notr:
	s_cmp_eq_u32 s24, 2
	s_cbranch_scc1 .LBB0_259
	s_cmp_eq_u32 s24, 7
	s_cbranch_scc1 .LBB0_259
	s_cmp_ge_u32 s24, 3
	s_cselect_b32 s2, 1, 0
	s_sub_u32 s2, s24, s2
	s_cmp_ge_u32 s24, 8
	s_cselect_b32 s3, 1, 0
	s_sub_u32 s2, s2, s3
	s_lshl_b32 s2, s2, 9
	s_add_u32 s2, s2, s0
	s_lshl_b32 s2, s2, 1
	s_mul_i32 s3, s1, 0x1c00
	s_add_u32 s2, s2, s3
	s_add_u32 s98, s90, 0x3971900
	s_addc_u32 s99, s91, 0
	s_add_u32 s98, s98, s2
	s_addc_u32 s99, s99, 0
	v_and_b32_e32 v120, 1, v118
	v_lshrrev_b32_e32 v121, 5, v118
	v_lshl_add_u32 v121, v121, 2, v120
	v_mul_u32_u24_e32 v121, 0x1c00, v121
	v_and_b32_e32 v122, 30, v118
	v_lshl_add_u32 v121, v122, 1, v121
	v_cmp_eq_u32_e32 vcc, 1, v120
	v_mov_b32_e32 v120, 0x05040100
	v_mov_b32_e32 v122, 0x03020706
	s_nop 1
	v_cndmask_b32_e32 v120, v120, v122, vcc
	v_cvt_pk_bf16_f32 v64, v48, v49
	v_cvt_pk_bf16_f32 v65, v50, v51
	v_cvt_pk_bf16_f32 v66, v52, v53
	v_cvt_pk_bf16_f32 v67, v54, v55
	v_cvt_pk_bf16_f32 v68, v56, v57
	v_cvt_pk_bf16_f32 v69, v58, v59
	v_cvt_pk_bf16_f32 v70, v60, v61
	v_cvt_pk_bf16_f32 v71, v62, v63
	v_cvt_pk_bf16_f32 v72, v16, v17
	v_cvt_pk_bf16_f32 v73, v18, v19
	v_cvt_pk_bf16_f32 v74, v20, v21
	v_cvt_pk_bf16_f32 v75, v22, v23
	v_cvt_pk_bf16_f32 v76, v24, v25
	v_cvt_pk_bf16_f32 v77, v26, v27
	v_cvt_pk_bf16_f32 v78, v28, v29
	v_cvt_pk_bf16_f32 v79, v30, v31
	v_mov_b32_dpp v80, v64 quad_perm:[1,0,3,2] row_mask:0xf bank_mask:0xf
	v_mov_b32_dpp v81, v65 quad_perm:[1,0,3,2] row_mask:0xf bank_mask:0xf
	v_mov_b32_dpp v82, v66 quad_perm:[1,0,3,2] row_mask:0xf bank_mask:0xf
	v_mov_b32_dpp v83, v67 quad_perm:[1,0,3,2] row_mask:0xf bank_mask:0xf
	v_mov_b32_dpp v84, v68 quad_perm:[1,0,3,2] row_mask:0xf bank_mask:0xf
	v_mov_b32_dpp v85, v69 quad_perm:[1,0,3,2] row_mask:0xf bank_mask:0xf
	v_mov_b32_dpp v86, v70 quad_perm:[1,0,3,2] row_mask:0xf bank_mask:0xf
	v_mov_b32_dpp v87, v71 quad_perm:[1,0,3,2] row_mask:0xf bank_mask:0xf
	v_mov_b32_dpp v88, v72 quad_perm:[1,0,3,2] row_mask:0xf bank_mask:0xf
	v_mov_b32_dpp v89, v73 quad_perm:[1,0,3,2] row_mask:0xf bank_mask:0xf
	v_mov_b32_dpp v90, v74 quad_perm:[1,0,3,2] row_mask:0xf bank_mask:0xf
	v_mov_b32_dpp v91, v75 quad_perm:[1,0,3,2] row_mask:0xf bank_mask:0xf
	v_mov_b32_dpp v92, v76 quad_perm:[1,0,3,2] row_mask:0xf bank_mask:0xf
	v_mov_b32_dpp v93, v77 quad_perm:[1,0,3,2] row_mask:0xf bank_mask:0xf
	v_mov_b32_dpp v94, v78 quad_perm:[1,0,3,2] row_mask:0xf bank_mask:0xf
	v_mov_b32_dpp v95, v79 quad_perm:[1,0,3,2] row_mask:0xf bank_mask:0xf
	v_perm_b32 v96, v80, v64, v120
	v_perm_b32 v97, v81, v65, v120
	v_perm_b32 v98, v82, v66, v120
	v_perm_b32 v99, v83, v67, v120
	v_perm_b32 v100, v84, v68, v120
	v_perm_b32 v101, v85, v69, v120
	v_perm_b32 v102, v86, v70, v120
	v_perm_b32 v103, v87, v71, v120
	v_perm_b32 v104, v88, v72, v120
	v_perm_b32 v105, v89, v73, v120
	v_perm_b32 v106, v90, v74, v120
	v_perm_b32 v107, v91, v75, v120
	v_perm_b32 v108, v92, v76, v120
	v_perm_b32 v109, v93, v77, v120
	v_perm_b32 v110, v94, v78, v120
	v_perm_b32 v111, v95, v79, v120
	global_store_dword v121, v96, s[98:99]
	global_store_dword v121, v104, s[98:99] offset:64
	s_add_u32 s98, s98, 0x3800
	s_addc_u32 s99, s99, 0
	global_store_dword v121, v97, s[98:99]
	global_store_dword v121, v105, s[98:99] offset:64
	s_add_u32 s98, s98, 0xa800
	s_addc_u32 s99, s99, 0
	global_store_dword v121, v98, s[98:99]
	global_store_dword v121, v106, s[98:99] offset:64
	s_add_u32 s98, s98, 0x3800
	s_addc_u32 s99, s99, 0
	global_store_dword v121, v99, s[98:99]
	global_store_dword v121, v107, s[98:99] offset:64
	s_add_u32 s98, s98, 0xa800
	s_addc_u32 s99, s99, 0
	global_store_dword v121, v100, s[98:99]
	global_store_dword v121, v108, s[98:99] offset:64
	s_add_u32 s98, s98, 0x3800
	s_addc_u32 s99, s99, 0
	global_store_dword v121, v101, s[98:99]
	global_store_dword v121, v109, s[98:99] offset:64
	s_add_u32 s98, s98, 0xa800
	s_addc_u32 s99, s99, 0
	global_store_dword v121, v102, s[98:99]
	global_store_dword v121, v110, s[98:99] offset:64
	s_add_u32 s98, s98, 0x3800
	s_addc_u32 s99, s99, 0
	global_store_dword v121, v103, s[98:99]
	global_store_dword v121, v111, s[98:99] offset:64
	s_add_u32 s98, s98, 0xa800
	s_addc_u32 s99, s99, 0
	v_cvt_pk_bf16_f32 v64, v32, v33
	v_cvt_pk_bf16_f32 v65, v34, v35
	v_cvt_pk_bf16_f32 v66, v36, v37
	v_cvt_pk_bf16_f32 v67, v38, v39
	v_cvt_pk_bf16_f32 v68, v40, v41
	v_cvt_pk_bf16_f32 v69, v42, v43
	v_cvt_pk_bf16_f32 v70, v44, v45
	v_cvt_pk_bf16_f32 v71, v46, v47
	v_cvt_pk_bf16_f32 v72, v0, v1
	v_cvt_pk_bf16_f32 v73, v2, v3
	v_cvt_pk_bf16_f32 v74, v4, v5
	v_cvt_pk_bf16_f32 v75, v6, v7
	v_cvt_pk_bf16_f32 v76, v8, v9
	v_cvt_pk_bf16_f32 v77, v10, v11
	v_cvt_pk_bf16_f32 v78, v12, v13
	v_cvt_pk_bf16_f32 v79, v14, v15
	v_mov_b32_dpp v80, v64 quad_perm:[1,0,3,2] row_mask:0xf bank_mask:0xf
	v_mov_b32_dpp v81, v65 quad_perm:[1,0,3,2] row_mask:0xf bank_mask:0xf
	v_mov_b32_dpp v82, v66 quad_perm:[1,0,3,2] row_mask:0xf bank_mask:0xf
	v_mov_b32_dpp v83, v67 quad_perm:[1,0,3,2] row_mask:0xf bank_mask:0xf
	v_mov_b32_dpp v84, v68 quad_perm:[1,0,3,2] row_mask:0xf bank_mask:0xf
	v_mov_b32_dpp v85, v69 quad_perm:[1,0,3,2] row_mask:0xf bank_mask:0xf
	v_mov_b32_dpp v86, v70 quad_perm:[1,0,3,2] row_mask:0xf bank_mask:0xf
	v_mov_b32_dpp v87, v71 quad_perm:[1,0,3,2] row_mask:0xf bank_mask:0xf
	v_mov_b32_dpp v88, v72 quad_perm:[1,0,3,2] row_mask:0xf bank_mask:0xf
	v_mov_b32_dpp v89, v73 quad_perm:[1,0,3,2] row_mask:0xf bank_mask:0xf
	v_mov_b32_dpp v90, v74 quad_perm:[1,0,3,2] row_mask:0xf bank_mask:0xf
	v_mov_b32_dpp v91, v75 quad_perm:[1,0,3,2] row_mask:0xf bank_mask:0xf
	v_mov_b32_dpp v92, v76 quad_perm:[1,0,3,2] row_mask:0xf bank_mask:0xf
	v_mov_b32_dpp v93, v77 quad_perm:[1,0,3,2] row_mask:0xf bank_mask:0xf
	v_mov_b32_dpp v94, v78 quad_perm:[1,0,3,2] row_mask:0xf bank_mask:0xf
	v_mov_b32_dpp v95, v79 quad_perm:[1,0,3,2] row_mask:0xf bank_mask:0xf
	v_perm_b32 v96, v80, v64, v120
	v_perm_b32 v97, v81, v65, v120
	v_perm_b32 v98, v82, v66, v120
	v_perm_b32 v99, v83, v67, v120
	v_perm_b32 v100, v84, v68, v120
	v_perm_b32 v101, v85, v69, v120
	v_perm_b32 v102, v86, v70, v120
	v_perm_b32 v103, v87, v71, v120
	v_perm_b32 v104, v88, v72, v120
	v_perm_b32 v105, v89, v73, v120
	v_perm_b32 v106, v90, v74, v120
	v_perm_b32 v107, v91, v75, v120
	v_perm_b32 v108, v92, v76, v120
	v_perm_b32 v109, v93, v77, v120
	v_perm_b32 v110, v94, v78, v120
	v_perm_b32 v111, v95, v79, v120
	global_store_dword v121, v96, s[98:99]
	global_store_dword v121, v104, s[98:99] offset:64
	s_add_u32 s98, s98, 0x3800
	s_addc_u32 s99, s99, 0
	global_store_dword v121, v97, s[98:99]
	global_store_dword v121, v105, s[98:99] offset:64
	s_add_u32 s98, s98, 0xa800
	s_addc_u32 s99, s99, 0
	global_store_dword v121, v98, s[98:99]
	global_store_dword v121, v106, s[98:99] offset:64
	s_add_u32 s98, s98, 0x3800
	s_addc_u32 s99, s99, 0
	global_store_dword v121, v99, s[98:99]
	global_store_dword v121, v107, s[98:99] offset:64
	s_add_u32 s98, s98, 0xa800
	s_addc_u32 s99, s99, 0
	global_store_dword v121, v100, s[98:99]
	global_store_dword v121, v108, s[98:99] offset:64
	s_add_u32 s98, s98, 0x3800
	s_addc_u32 s99, s99, 0
	global_store_dword v121, v101, s[98:99]
	global_store_dword v121, v109, s[98:99] offset:64
	s_add_u32 s98, s98, 0xa800
	s_addc_u32 s99, s99, 0
	global_store_dword v121, v102, s[98:99]
	global_store_dword v121, v110, s[98:99] offset:64
	s_add_u32 s98, s98, 0x3800
	s_addc_u32 s99, s99, 0
	global_store_dword v121, v103, s[98:99]
	global_store_dword v121, v111, s[98:99] offset:64
	s_add_u32 s98, s98, 0xa800
	s_addc_u32 s99, s99, 0
	s_branch .LBB0_259

.Lodin4_nat:
	s_lshl_b32 s8, s7, 11
	s_add_u32 s8, s8, s9
	s_lshl_b32 s9, s6, 1
	s_add_u32 s8, s8, s9
	s_add_u32 s98, s90, s8
	s_addc_u32 s99, s91, 0
	v_and_b32_e32 v120, 1, v118
	v_lshrrev_b32_e32 v121, 5, v118
	v_lshl_add_u32 v121, v121, 2, v120
	v_mul_u32_u24_e32 v121, 0x800, v121
	v_and_b32_e32 v122, 30, v118
	v_lshl_add_u32 v121, v122, 1, v121
	v_cmp_eq_u32_e32 vcc, 1, v120
	v_mov_b32_e32 v120, 0x05040100
	v_mov_b32_e32 v122, 0x03020706
	s_nop 1
	v_cndmask_b32_e32 v120, v120, v122, vcc
	v_cvt_pk_bf16_f32 v64, v48, v49
	v_cvt_pk_bf16_f32 v65, v50, v51
	v_cvt_pk_bf16_f32 v66, v52, v53
	v_cvt_pk_bf16_f32 v67, v54, v55
	v_cvt_pk_bf16_f32 v68, v56, v57
	v_cvt_pk_bf16_f32 v69, v58, v59
	v_cvt_pk_bf16_f32 v70, v60, v61
	v_cvt_pk_bf16_f32 v71, v62, v63
	v_cvt_pk_bf16_f32 v72, v16, v17
	v_cvt_pk_bf16_f32 v73, v18, v19
	v_cvt_pk_bf16_f32 v74, v20, v21
	v_cvt_pk_bf16_f32 v75, v22, v23
	v_cvt_pk_bf16_f32 v76, v24, v25
	v_cvt_pk_bf16_f32 v77, v26, v27
	v_cvt_pk_bf16_f32 v78, v28, v29
	v_cvt_pk_bf16_f32 v79, v30, v31
	v_mov_b32_dpp v80, v64 quad_perm:[1,0,3,2] row_mask:0xf bank_mask:0xf
	v_mov_b32_dpp v81, v65 quad_perm:[1,0,3,2] row_mask:0xf bank_mask:0xf
	v_mov_b32_dpp v82, v66 quad_perm:[1,0,3,2] row_mask:0xf bank_mask:0xf
	v_mov_b32_dpp v83, v67 quad_perm:[1,0,3,2] row_mask:0xf bank_mask:0xf
	v_mov_b32_dpp v84, v68 quad_perm:[1,0,3,2] row_mask:0xf bank_mask:0xf
	v_mov_b32_dpp v85, v69 quad_perm:[1,0,3,2] row_mask:0xf bank_mask:0xf
	v_mov_b32_dpp v86, v70 quad_perm:[1,0,3,2] row_mask:0xf bank_mask:0xf
	v_mov_b32_dpp v87, v71 quad_perm:[1,0,3,2] row_mask:0xf bank_mask:0xf
	v_mov_b32_dpp v88, v72 quad_perm:[1,0,3,2] row_mask:0xf bank_mask:0xf
	v_mov_b32_dpp v89, v73 quad_perm:[1,0,3,2] row_mask:0xf bank_mask:0xf
	v_mov_b32_dpp v90, v74 quad_perm:[1,0,3,2] row_mask:0xf bank_mask:0xf
	v_mov_b32_dpp v91, v75 quad_perm:[1,0,3,2] row_mask:0xf bank_mask:0xf
	v_mov_b32_dpp v92, v76 quad_perm:[1,0,3,2] row_mask:0xf bank_mask:0xf
	v_mov_b32_dpp v93, v77 quad_perm:[1,0,3,2] row_mask:0xf bank_mask:0xf
	v_mov_b32_dpp v94, v78 quad_perm:[1,0,3,2] row_mask:0xf bank_mask:0xf
	v_mov_b32_dpp v95, v79 quad_perm:[1,0,3,2] row_mask:0xf bank_mask:0xf
	v_perm_b32 v96, v80, v64, v120
	v_perm_b32 v97, v81, v65, v120
	v_perm_b32 v98, v82, v66, v120
	v_perm_b32 v99, v83, v67, v120
	v_perm_b32 v100, v84, v68, v120
	v_perm_b32 v101, v85, v69, v120
	v_perm_b32 v102, v86, v70, v120
	v_perm_b32 v103, v87, v71, v120
	v_perm_b32 v104, v88, v72, v120
	v_perm_b32 v105, v89, v73, v120
	v_perm_b32 v106, v90, v74, v120
	v_perm_b32 v107, v91, v75, v120
	v_perm_b32 v108, v92, v76, v120
	v_perm_b32 v109, v93, v77, v120
	v_perm_b32 v110, v94, v78, v120
	v_perm_b32 v111, v95, v79, v120
	global_store_dword v121, v96, s[98:99]
	global_store_dword v121, v104, s[98:99] offset:64
	s_add_u32 s98, s98, 0x1000
	s_addc_u32 s99, s99, 0
	global_store_dword v121, v97, s[98:99]
	global_store_dword v121, v105, s[98:99] offset:64
	s_add_u32 s98, s98, 0x3000
	s_addc_u32 s99, s99, 0
	global_store_dword v121, v98, s[98:99]
	global_store_dword v121, v106, s[98:99] offset:64
	s_add_u32 s98, s98, 0x1000
	s_addc_u32 s99, s99, 0
	global_store_dword v121, v99, s[98:99]
	global_store_dword v121, v107, s[98:99] offset:64
	s_add_u32 s98, s98, 0x3000
	s_addc_u32 s99, s99, 0
	global_store_dword v121, v100, s[98:99]
	global_store_dword v121, v108, s[98:99] offset:64
	s_add_u32 s98, s98, 0x1000
	s_addc_u32 s99, s99, 0
	global_store_dword v121, v101, s[98:99]
	global_store_dword v121, v109, s[98:99] offset:64
	s_add_u32 s98, s98, 0x3000
	s_addc_u32 s99, s99, 0
	global_store_dword v121, v102, s[98:99]
	global_store_dword v121, v110, s[98:99] offset:64
	s_add_u32 s98, s98, 0x1000
	s_addc_u32 s99, s99, 0
	global_store_dword v121, v103, s[98:99]
	global_store_dword v121, v111, s[98:99] offset:64
	s_add_u32 s98, s98, 0x3000
	s_addc_u32 s99, s99, 0
	v_cvt_pk_bf16_f32 v64, v32, v33
	v_cvt_pk_bf16_f32 v65, v34, v35
	v_cvt_pk_bf16_f32 v66, v36, v37
	v_cvt_pk_bf16_f32 v67, v38, v39
	v_cvt_pk_bf16_f32 v68, v40, v41
	v_cvt_pk_bf16_f32 v69, v42, v43
	v_cvt_pk_bf16_f32 v70, v44, v45
	v_cvt_pk_bf16_f32 v71, v46, v47
	v_cvt_pk_bf16_f32 v72, v0, v1
	v_cvt_pk_bf16_f32 v73, v2, v3
	v_cvt_pk_bf16_f32 v74, v4, v5
	v_cvt_pk_bf16_f32 v75, v6, v7
	v_cvt_pk_bf16_f32 v76, v8, v9
	v_cvt_pk_bf16_f32 v77, v10, v11
	v_cvt_pk_bf16_f32 v78, v12, v13
	v_cvt_pk_bf16_f32 v79, v14, v15
	v_mov_b32_dpp v80, v64 quad_perm:[1,0,3,2] row_mask:0xf bank_mask:0xf
	v_mov_b32_dpp v81, v65 quad_perm:[1,0,3,2] row_mask:0xf bank_mask:0xf
	v_mov_b32_dpp v82, v66 quad_perm:[1,0,3,2] row_mask:0xf bank_mask:0xf
	v_mov_b32_dpp v83, v67 quad_perm:[1,0,3,2] row_mask:0xf bank_mask:0xf
	v_mov_b32_dpp v84, v68 quad_perm:[1,0,3,2] row_mask:0xf bank_mask:0xf
	v_mov_b32_dpp v85, v69 quad_perm:[1,0,3,2] row_mask:0xf bank_mask:0xf
	v_mov_b32_dpp v86, v70 quad_perm:[1,0,3,2] row_mask:0xf bank_mask:0xf
	v_mov_b32_dpp v87, v71 quad_perm:[1,0,3,2] row_mask:0xf bank_mask:0xf
	v_mov_b32_dpp v88, v72 quad_perm:[1,0,3,2] row_mask:0xf bank_mask:0xf
	v_mov_b32_dpp v89, v73 quad_perm:[1,0,3,2] row_mask:0xf bank_mask:0xf
	v_mov_b32_dpp v90, v74 quad_perm:[1,0,3,2] row_mask:0xf bank_mask:0xf
	v_mov_b32_dpp v91, v75 quad_perm:[1,0,3,2] row_mask:0xf bank_mask:0xf
	v_mov_b32_dpp v92, v76 quad_perm:[1,0,3,2] row_mask:0xf bank_mask:0xf
	v_mov_b32_dpp v93, v77 quad_perm:[1,0,3,2] row_mask:0xf bank_mask:0xf
	v_mov_b32_dpp v94, v78 quad_perm:[1,0,3,2] row_mask:0xf bank_mask:0xf
	v_mov_b32_dpp v95, v79 quad_perm:[1,0,3,2] row_mask:0xf bank_mask:0xf
	v_perm_b32 v96, v80, v64, v120
	v_perm_b32 v97, v81, v65, v120
	v_perm_b32 v98, v82, v66, v120
	v_perm_b32 v99, v83, v67, v120
	v_perm_b32 v100, v84, v68, v120
	v_perm_b32 v101, v85, v69, v120
	v_perm_b32 v102, v86, v70, v120
	v_perm_b32 v103, v87, v71, v120
	v_perm_b32 v104, v88, v72, v120
	v_perm_b32 v105, v89, v73, v120
	v_perm_b32 v106, v90, v74, v120
	v_perm_b32 v107, v91, v75, v120
	v_perm_b32 v108, v92, v76, v120
	v_perm_b32 v109, v93, v77, v120
	v_perm_b32 v110, v94, v78, v120
	v_perm_b32 v111, v95, v79, v120
	global_store_dword v121, v96, s[98:99]
	global_store_dword v121, v104, s[98:99] offset:64
	s_add_u32 s98, s98, 0x1000
	s_addc_u32 s99, s99, 0
	global_store_dword v121, v97, s[98:99]
	global_store_dword v121, v105, s[98:99] offset:64
	s_add_u32 s98, s98, 0x3000
	s_addc_u32 s99, s99, 0
	global_store_dword v121, v98, s[98:99]
	global_store_dword v121, v106, s[98:99] offset:64
	s_add_u32 s98, s98, 0x1000
	s_addc_u32 s99, s99, 0
	global_store_dword v121, v99, s[98:99]
	global_store_dword v121, v107, s[98:99] offset:64
	s_add_u32 s98, s98, 0x3000
	s_addc_u32 s99, s99, 0
	global_store_dword v121, v100, s[98:99]
	global_store_dword v121, v108, s[98:99] offset:64
	s_add_u32 s98, s98, 0x1000
	s_addc_u32 s99, s99, 0
	global_store_dword v121, v101, s[98:99]
	global_store_dword v121, v109, s[98:99] offset:64
	s_add_u32 s98, s98, 0x3000
	s_addc_u32 s99, s99, 0
	global_store_dword v121, v102, s[98:99]
	global_store_dword v121, v110, s[98:99] offset:64
	s_add_u32 s98, s98, 0x1000
	s_addc_u32 s99, s99, 0
	global_store_dword v121, v103, s[98:99]
	global_store_dword v121, v111, s[98:99] offset:64
	s_add_u32 s98, s98, 0x3000
	s_addc_u32 s99, s99, 0
	s_branch .Lodin4_next
